# decode pass 2 rewritten by hand: ten keys (20 loads) in flight per wave through rotating slots, fixed accumulators, weights read one key ahead
# baseline (speedup 1.0000x reference)
; #define DEC_LOADV(dst, i0) do { asm volatile("" ::: "memory"); _Pragma("unroll") for (int u = 0; u < 4; ++u) { const float* vr = cv + rbase + (size_t)((i0) + u) * 512; dst[u][0] = __builtin_nontemporal_load((const f32x4*)(vr + 4 * lane)); dst[u][1] = __builtin_nontemporal_load((const f32x4*)(vr + 256 + 4 * lane)); } } while (0)
; __device__ __forceinline__ void decode_item(Frame& F, const Args& a, int l, int item, unsigned char* ws) {
;     ...
;     f32x4 O[4][2];
; #pragma unroll
;     for (int qi = 0; qi < 4; ++qi) { O[qi][0] = (f32x4){0.f, 0.f, 0.f, 0.f}; O[qi][1] = O[qi][0]; }
;     const int hh = lane >> 5;
;     {
;         f32x4 va[4][2], vb[4][2];
;     ...
;         DEC_LOADV(va, 0); DEC_LOADV(vb, 4); DEC_ACC(va, 0); DEC_LOADV(va, 8); DEC_ACC(vb, 4); DEC_LOADV(vb, 12); DEC_ACC(va, 8); DEC_LOADV(va, 16); DEC_ACC(vb, 12); DEC_LOADV(vb, 20); DEC_ACC(va, 16); DEC_LOADV(va, 24); DEC_ACC(vb, 20); DEC_LOADV(vb, 28); DEC_ACC(va, 24); DEC_ACC(vb, 28);
.LBB0_1221:
	s_or_b64 exec, exec, s[0:1]
	v_readlane_b32 s36, v252, 21
	v_readlane_b32 s42, v252, 27
	v_readlane_b32 s43, v252, 28
	s_add_u32 s0, s42, s6
	s_addc_u32 s1, s43, s7
	v_lshl_add_u64 v[2:3], v[118:119], 2, s[0:1]
	s_waitcnt lgkmcnt(0)
	s_waitcnt lgkmcnt(0)
	s_barrier
	v_lshl_add_u64 v[86:87], v[116:117], 2, v[2:3]
	v_lshlrev_b32_e64 v34, 11, s18
	v_and_b32_e32 v14, 0xffffffe0, v122
	s_nop 0
	v_add3_u32 v34, 0, v34, v14
	global_load_dwordx4 v[52:55], v[86:87], off nt
	global_load_dwordx4 v[56:59], v[86:87], off offset:1024 nt
	global_load_dwordx4 v[60:63], v[86:87], off offset:2048 nt
	global_load_dwordx4 v[64:67], v[86:87], off offset:3072 nt
	v_add_co_u32_e32 v86, vcc, 0x1000, v86
	s_nop 1
	v_addc_co_u32_e32 v87, vcc, 0, v87, vcc
	global_load_dwordx4 v[68:71], v[86:87], off nt
	global_load_dwordx4 v[72:75], v[86:87], off offset:1024 nt
	global_load_dwordx4 v[76:79], v[86:87], off offset:2048 nt
	global_load_dwordx4 v[80:83], v[86:87], off offset:3072 nt
	v_add_co_u32_e32 v86, vcc, 0x1000, v86
	s_nop 1
	v_addc_co_u32_e32 v87, vcc, 0, v87, vcc
	global_load_dwordx4 v[88:91], v[86:87], off nt
	global_load_dwordx4 v[92:95], v[86:87], off offset:1024 nt
	global_load_dwordx4 v[96:99], v[86:87], off offset:2048 nt
	global_load_dwordx4 v[100:103], v[86:87], off offset:3072 nt
	v_add_co_u32_e32 v86, vcc, 0x1000, v86
	s_nop 1
	v_addc_co_u32_e32 v87, vcc, 0, v87, vcc
	global_load_dwordx4 v[104:107], v[86:87], off nt
	global_load_dwordx4 v[108:111], v[86:87], off offset:1024 nt
	global_load_dwordx4 v[184:187], v[86:87], off offset:2048 nt
	global_load_dwordx4 v[188:191], v[86:87], off offset:3072 nt
	v_add_co_u32_e32 v86, vcc, 0x1000, v86
	s_nop 1
	v_addc_co_u32_e32 v87, vcc, 0, v87, vcc
	global_load_dwordx4 v[192:195], v[86:87], off nt
	global_load_dwordx4 v[196:199], v[86:87], off offset:1024 nt
	global_load_dwordx4 v[200:203], v[86:87], off offset:2048 nt
	global_load_dwordx4 v[204:207], v[86:87], off offset:3072 nt
	v_add_co_u32_e32 v86, vcc, 0x1000, v86
	s_nop 1
	v_addc_co_u32_e32 v87, vcc, 0, v87, vcc
	ds_read_b128 v[14:17], v34 offset:16384
	ds_read_b128 v[40:43], v34 offset:16400
	v_readlane_b32 s37, v252, 22
	v_readlane_b32 s38, v252, 23
	v_readlane_b32 s39, v252, 24
	v_readlane_b32 s40, v252, 25
	v_readlane_b32 s41, v252, 26
	v_readlane_b32 s44, v252, 29
	v_readlane_b32 s45, v252, 30
	v_readlane_b32 s46, v252, 31
	v_readlane_b32 s47, v252, 32
	v_readlane_b32 s48, v252, 33
	v_readlane_b32 s49, v252, 34
	v_readlane_b32 s50, v252, 35
	v_readlane_b32 s51, v252, 36
	ds_read_b128 v[44:47], v34 offset:16448
	ds_read_b128 v[48:51], v34 offset:16464
	s_waitcnt vmcnt(18) lgkmcnt(2)
	v_pk_fma_f32 v[18:19], v[52:53], v[14:15], 0 op_sel_hi:[1,0,0]
	v_pk_fma_f32 v[20:21], v[54:55], v[14:15], 0 op_sel_hi:[1,0,0]
	v_pk_fma_f32 v[22:23], v[56:57], v[14:15], 0 op_sel:[0,1,0] op_sel_hi:[1,1,0]
	v_pk_fma_f32 v[24:25], v[58:59], v[14:15], 0 op_sel:[0,1,0] op_sel_hi:[1,1,0]
	v_pk_fma_f32 v[26:27], v[52:53], v[16:17], 0 op_sel_hi:[1,0,0]
	v_pk_fma_f32 v[28:29], v[54:55], v[16:17], 0 op_sel_hi:[1,0,0]
	v_pk_fma_f32 v[6:7], v[56:57], v[16:17], 0 op_sel:[0,1,0] op_sel_hi:[1,1,0]
	v_pk_fma_f32 v[8:9], v[58:59], v[16:17], 0 op_sel:[0,1,0] op_sel_hi:[1,1,0]
	v_pk_fma_f32 v[30:31], v[52:53], v[40:41], 0 op_sel_hi:[1,0,0]
	v_pk_fma_f32 v[32:33], v[54:55], v[40:41], 0 op_sel_hi:[1,0,0]
	v_pk_fma_f32 v[36:37], v[56:57], v[40:41], 0 op_sel:[0,1,0] op_sel_hi:[1,1,0]
	v_pk_fma_f32 v[38:39], v[58:59], v[40:41], 0 op_sel:[0,1,0] op_sel_hi:[1,1,0]
	v_pk_fma_f32 v[10:11], v[52:53], v[42:43], 0 op_sel_hi:[1,0,0]
	v_pk_fma_f32 v[12:13], v[54:55], v[42:43], 0 op_sel_hi:[1,0,0]
	v_pk_fma_f32 v[2:3], v[56:57], v[42:43], 0 op_sel:[0,1,0] op_sel_hi:[1,1,0]
	v_pk_fma_f32 v[4:5], v[58:59], v[42:43], 0 op_sel:[0,1,0] op_sel_hi:[1,1,0]
	global_load_dwordx4 v[52:55], v[86:87], off nt
	global_load_dwordx4 v[56:59], v[86:87], off offset:1024 nt
	ds_read_b128 v[14:17], v34 offset:16512
	ds_read_b128 v[40:43], v34 offset:16528
	s_waitcnt vmcnt(18) lgkmcnt(2)
	v_pk_fma_f32 v[18:19], v[60:61], v[44:45], v[18:19] op_sel_hi:[1,0,1]
	v_pk_fma_f32 v[20:21], v[62:63], v[44:45], v[20:21] op_sel_hi:[1,0,1]
	v_pk_fma_f32 v[22:23], v[64:65], v[44:45], v[22:23] op_sel:[0,1,0]
	v_pk_fma_f32 v[24:25], v[66:67], v[44:45], v[24:25] op_sel:[0,1,0]
	v_pk_fma_f32 v[26:27], v[60:61], v[46:47], v[26:27] op_sel_hi:[1,0,1]
	v_pk_fma_f32 v[28:29], v[62:63], v[46:47], v[28:29] op_sel_hi:[1,0,1]
	v_pk_fma_f32 v[6:7], v[64:65], v[46:47], v[6:7] op_sel:[0,1,0]
	v_pk_fma_f32 v[8:9], v[66:67], v[46:47], v[8:9] op_sel:[0,1,0]
	v_pk_fma_f32 v[30:31], v[60:61], v[48:49], v[30:31] op_sel_hi:[1,0,1]
	v_pk_fma_f32 v[32:33], v[62:63], v[48:49], v[32:33] op_sel_hi:[1,0,1]
	v_pk_fma_f32 v[36:37], v[64:65], v[48:49], v[36:37] op_sel:[0,1,0]
	v_pk_fma_f32 v[38:39], v[66:67], v[48:49], v[38:39] op_sel:[0,1,0]
	v_pk_fma_f32 v[10:11], v[60:61], v[50:51], v[10:11] op_sel_hi:[1,0,1]
	v_pk_fma_f32 v[12:13], v[62:63], v[50:51], v[12:13] op_sel_hi:[1,0,1]
	v_pk_fma_f32 v[2:3], v[64:65], v[50:51], v[2:3] op_sel:[0,1,0]
	v_pk_fma_f32 v[4:5], v[66:67], v[50:51], v[4:5] op_sel:[0,1,0]
	global_load_dwordx4 v[60:63], v[86:87], off offset:2048 nt
	global_load_dwordx4 v[64:67], v[86:87], off offset:3072 nt
	v_add_co_u32_e32 v86, vcc, 0x1000, v86
	s_nop 1
	v_addc_co_u32_e32 v87, vcc, 0, v87, vcc
	ds_read_b128 v[44:47], v34 offset:16576
	ds_read_b128 v[48:51], v34 offset:16592
	s_waitcnt vmcnt(18) lgkmcnt(2)
; #define DEC_LOADV(dst, i0) do { asm volatile("" ::: "memory"); _Pragma("unroll") for (int u = 0; u < 4; ++u) { const float* vr = cv + rbase + (size_t)((i0) + u) * 512; dst[u][0] = __builtin_nontemporal_load((const f32x4*)(vr + 4 * lane)); dst[u][1] = __builtin_nontemporal_load((const f32x4*)(vr + 256 + 4 * lane)); } } while (0)
; __device__ __forceinline__ void decode_item(Frame& F, const Args& a, int l, int item, unsigned char* ws) {
;     ...
;         DEC_LOADV(va, 0); DEC_LOADV(vb, 4); DEC_ACC(va, 0); DEC_LOADV(va, 8); DEC_ACC(vb, 4); DEC_LOADV(vb, 12); DEC_ACC(va, 8); DEC_LOADV(va, 16); DEC_ACC(vb, 12); DEC_LOADV(vb, 20); DEC_ACC(va, 16); DEC_LOADV(va, 24); DEC_ACC(vb, 20); DEC_LOADV(vb, 28); DEC_ACC(va, 24); DEC_ACC(vb, 28);
	v_pk_fma_f32 v[18:19], v[68:69], v[14:15], v[18:19] op_sel_hi:[1,0,1]
	v_pk_fma_f32 v[20:21], v[70:71], v[14:15], v[20:21] op_sel_hi:[1,0,1]
	v_pk_fma_f32 v[22:23], v[72:73], v[14:15], v[22:23] op_sel:[0,1,0]
	v_pk_fma_f32 v[24:25], v[74:75], v[14:15], v[24:25] op_sel:[0,1,0]
	v_pk_fma_f32 v[26:27], v[68:69], v[16:17], v[26:27] op_sel_hi:[1,0,1]
	v_pk_fma_f32 v[28:29], v[70:71], v[16:17], v[28:29] op_sel_hi:[1,0,1]
	v_pk_fma_f32 v[6:7], v[72:73], v[16:17], v[6:7] op_sel:[0,1,0]
	v_pk_fma_f32 v[8:9], v[74:75], v[16:17], v[8:9] op_sel:[0,1,0]
	v_pk_fma_f32 v[30:31], v[68:69], v[40:41], v[30:31] op_sel_hi:[1,0,1]
	v_pk_fma_f32 v[32:33], v[70:71], v[40:41], v[32:33] op_sel_hi:[1,0,1]
	v_pk_fma_f32 v[36:37], v[72:73], v[40:41], v[36:37] op_sel:[0,1,0]
	v_pk_fma_f32 v[38:39], v[74:75], v[40:41], v[38:39] op_sel:[0,1,0]
	v_pk_fma_f32 v[10:11], v[68:69], v[42:43], v[10:11] op_sel_hi:[1,0,1]
	v_pk_fma_f32 v[12:13], v[70:71], v[42:43], v[12:13] op_sel_hi:[1,0,1]
	v_pk_fma_f32 v[2:3], v[72:73], v[42:43], v[2:3] op_sel:[0,1,0]
	v_pk_fma_f32 v[4:5], v[74:75], v[42:43], v[4:5] op_sel:[0,1,0]
	global_load_dwordx4 v[68:71], v[86:87], off nt
	global_load_dwordx4 v[72:75], v[86:87], off offset:1024 nt
	ds_read_b128 v[14:17], v34 offset:16640
	ds_read_b128 v[40:43], v34 offset:16656
	s_waitcnt vmcnt(18) lgkmcnt(2)
	v_pk_fma_f32 v[18:19], v[76:77], v[44:45], v[18:19] op_sel_hi:[1,0,1]
	v_pk_fma_f32 v[20:21], v[78:79], v[44:45], v[20:21] op_sel_hi:[1,0,1]
	v_pk_fma_f32 v[22:23], v[80:81], v[44:45], v[22:23] op_sel:[0,1,0]
	v_pk_fma_f32 v[24:25], v[82:83], v[44:45], v[24:25] op_sel:[0,1,0]
	v_pk_fma_f32 v[26:27], v[76:77], v[46:47], v[26:27] op_sel_hi:[1,0,1]
	v_pk_fma_f32 v[28:29], v[78:79], v[46:47], v[28:29] op_sel_hi:[1,0,1]
	v_pk_fma_f32 v[6:7], v[80:81], v[46:47], v[6:7] op_sel:[0,1,0]
	v_pk_fma_f32 v[8:9], v[82:83], v[46:47], v[8:9] op_sel:[0,1,0]
	v_pk_fma_f32 v[30:31], v[76:77], v[48:49], v[30:31] op_sel_hi:[1,0,1]
	v_pk_fma_f32 v[32:33], v[78:79], v[48:49], v[32:33] op_sel_hi:[1,0,1]
	v_pk_fma_f32 v[36:37], v[80:81], v[48:49], v[36:37] op_sel:[0,1,0]
	v_pk_fma_f32 v[38:39], v[82:83], v[48:49], v[38:39] op_sel:[0,1,0]
	v_pk_fma_f32 v[10:11], v[76:77], v[50:51], v[10:11] op_sel_hi:[1,0,1]
	v_pk_fma_f32 v[12:13], v[78:79], v[50:51], v[12:13] op_sel_hi:[1,0,1]
	v_pk_fma_f32 v[2:3], v[80:81], v[50:51], v[2:3] op_sel:[0,1,0]
	v_pk_fma_f32 v[4:5], v[82:83], v[50:51], v[4:5] op_sel:[0,1,0]
	global_load_dwordx4 v[76:79], v[86:87], off offset:2048 nt
	global_load_dwordx4 v[80:83], v[86:87], off offset:3072 nt
	v_add_co_u32_e32 v86, vcc, 0x1000, v86
	s_nop 1
	v_addc_co_u32_e32 v87, vcc, 0, v87, vcc
	ds_read_b128 v[44:47], v34 offset:16704
	ds_read_b128 v[48:51], v34 offset:16720
	s_waitcnt vmcnt(18) lgkmcnt(2)
	v_pk_fma_f32 v[18:19], v[88:89], v[14:15], v[18:19] op_sel_hi:[1,0,1]
	v_pk_fma_f32 v[20:21], v[90:91], v[14:15], v[20:21] op_sel_hi:[1,0,1]
	v_pk_fma_f32 v[22:23], v[92:93], v[14:15], v[22:23] op_sel:[0,1,0]
	v_pk_fma_f32 v[24:25], v[94:95], v[14:15], v[24:25] op_sel:[0,1,0]
	v_pk_fma_f32 v[26:27], v[88:89], v[16:17], v[26:27] op_sel_hi:[1,0,1]
	v_pk_fma_f32 v[28:29], v[90:91], v[16:17], v[28:29] op_sel_hi:[1,0,1]
	v_pk_fma_f32 v[6:7], v[92:93], v[16:17], v[6:7] op_sel:[0,1,0]
	v_pk_fma_f32 v[8:9], v[94:95], v[16:17], v[8:9] op_sel:[0,1,0]
	v_pk_fma_f32 v[30:31], v[88:89], v[40:41], v[30:31] op_sel_hi:[1,0,1]
	v_pk_fma_f32 v[32:33], v[90:91], v[40:41], v[32:33] op_sel_hi:[1,0,1]
	v_pk_fma_f32 v[36:37], v[92:93], v[40:41], v[36:37] op_sel:[0,1,0]
	v_pk_fma_f32 v[38:39], v[94:95], v[40:41], v[38:39] op_sel:[0,1,0]
	v_pk_fma_f32 v[10:11], v[88:89], v[42:43], v[10:11] op_sel_hi:[1,0,1]
	v_pk_fma_f32 v[12:13], v[90:91], v[42:43], v[12:13] op_sel_hi:[1,0,1]
	v_pk_fma_f32 v[2:3], v[92:93], v[42:43], v[2:3] op_sel:[0,1,0]
	v_pk_fma_f32 v[4:5], v[94:95], v[42:43], v[4:5] op_sel:[0,1,0]
	global_load_dwordx4 v[88:91], v[86:87], off nt
	global_load_dwordx4 v[92:95], v[86:87], off offset:1024 nt
	ds_read_b128 v[14:17], v34 offset:16768
	ds_read_b128 v[40:43], v34 offset:16784
	s_waitcnt vmcnt(18) lgkmcnt(2)
	v_pk_fma_f32 v[18:19], v[96:97], v[44:45], v[18:19] op_sel_hi:[1,0,1]
	v_pk_fma_f32 v[20:21], v[98:99], v[44:45], v[20:21] op_sel_hi:[1,0,1]
	v_pk_fma_f32 v[22:23], v[100:101], v[44:45], v[22:23] op_sel:[0,1,0]
	v_pk_fma_f32 v[24:25], v[102:103], v[44:45], v[24:25] op_sel:[0,1,0]
	v_pk_fma_f32 v[26:27], v[96:97], v[46:47], v[26:27] op_sel_hi:[1,0,1]
	v_pk_fma_f32 v[28:29], v[98:99], v[46:47], v[28:29] op_sel_hi:[1,0,1]
	v_pk_fma_f32 v[6:7], v[100:101], v[46:47], v[6:7] op_sel:[0,1,0]
	v_pk_fma_f32 v[8:9], v[102:103], v[46:47], v[8:9] op_sel:[0,1,0]
	v_pk_fma_f32 v[30:31], v[96:97], v[48:49], v[30:31] op_sel_hi:[1,0,1]
	v_pk_fma_f32 v[32:33], v[98:99], v[48:49], v[32:33] op_sel_hi:[1,0,1]
	v_pk_fma_f32 v[36:37], v[100:101], v[48:49], v[36:37] op_sel:[0,1,0]
	v_pk_fma_f32 v[38:39], v[102:103], v[48:49], v[38:39] op_sel:[0,1,0]
	v_pk_fma_f32 v[10:11], v[96:97], v[50:51], v[10:11] op_sel_hi:[1,0,1]
	v_pk_fma_f32 v[12:13], v[98:99], v[50:51], v[12:13] op_sel_hi:[1,0,1]
	v_pk_fma_f32 v[2:3], v[100:101], v[50:51], v[2:3] op_sel:[0,1,0]
	v_pk_fma_f32 v[4:5], v[102:103], v[50:51], v[4:5] op_sel:[0,1,0]
	global_load_dwordx4 v[96:99], v[86:87], off offset:2048 nt
	global_load_dwordx4 v[100:103], v[86:87], off offset:3072 nt
	v_add_co_u32_e32 v86, vcc, 0x1000, v86
	s_nop 1
	v_addc_co_u32_e32 v87, vcc, 0, v87, vcc
	ds_read_b128 v[44:47], v34 offset:16832
	ds_read_b128 v[48:51], v34 offset:16848
	s_waitcnt vmcnt(18) lgkmcnt(2)
; #define DEC_LOADV(dst, i0) do { asm volatile("" ::: "memory"); _Pragma("unroll") for (int u = 0; u < 4; ++u) { const float* vr = cv + rbase + (size_t)((i0) + u) * 512; dst[u][0] = __builtin_nontemporal_load((const f32x4*)(vr + 4 * lane)); dst[u][1] = __builtin_nontemporal_load((const f32x4*)(vr + 256 + 4 * lane)); } } while (0)
; __device__ __forceinline__ void decode_item(Frame& F, const Args& a, int l, int item, unsigned char* ws) {
;     ...
;         DEC_LOADV(va, 0); DEC_LOADV(vb, 4); DEC_ACC(va, 0); DEC_LOADV(va, 8); DEC_ACC(vb, 4); DEC_LOADV(vb, 12); DEC_ACC(va, 8); DEC_LOADV(va, 16); DEC_ACC(vb, 12); DEC_LOADV(vb, 20); DEC_ACC(va, 16); DEC_LOADV(va, 24); DEC_ACC(vb, 20); DEC_LOADV(vb, 28); DEC_ACC(va, 24); DEC_ACC(vb, 28);
	v_pk_fma_f32 v[18:19], v[104:105], v[14:15], v[18:19] op_sel_hi:[1,0,1]
	v_pk_fma_f32 v[20:21], v[106:107], v[14:15], v[20:21] op_sel_hi:[1,0,1]
	v_pk_fma_f32 v[22:23], v[108:109], v[14:15], v[22:23] op_sel:[0,1,0]
	v_pk_fma_f32 v[24:25], v[110:111], v[14:15], v[24:25] op_sel:[0,1,0]
	v_pk_fma_f32 v[26:27], v[104:105], v[16:17], v[26:27] op_sel_hi:[1,0,1]
	v_pk_fma_f32 v[28:29], v[106:107], v[16:17], v[28:29] op_sel_hi:[1,0,1]
	v_pk_fma_f32 v[6:7], v[108:109], v[16:17], v[6:7] op_sel:[0,1,0]
	v_pk_fma_f32 v[8:9], v[110:111], v[16:17], v[8:9] op_sel:[0,1,0]
	v_pk_fma_f32 v[30:31], v[104:105], v[40:41], v[30:31] op_sel_hi:[1,0,1]
	v_pk_fma_f32 v[32:33], v[106:107], v[40:41], v[32:33] op_sel_hi:[1,0,1]
	v_pk_fma_f32 v[36:37], v[108:109], v[40:41], v[36:37] op_sel:[0,1,0]
	v_pk_fma_f32 v[38:39], v[110:111], v[40:41], v[38:39] op_sel:[0,1,0]
	v_pk_fma_f32 v[10:11], v[104:105], v[42:43], v[10:11] op_sel_hi:[1,0,1]
	v_pk_fma_f32 v[12:13], v[106:107], v[42:43], v[12:13] op_sel_hi:[1,0,1]
	v_pk_fma_f32 v[2:3], v[108:109], v[42:43], v[2:3] op_sel:[0,1,0]
	v_pk_fma_f32 v[4:5], v[110:111], v[42:43], v[4:5] op_sel:[0,1,0]
	global_load_dwordx4 v[104:107], v[86:87], off nt
	global_load_dwordx4 v[108:111], v[86:87], off offset:1024 nt
	ds_read_b128 v[14:17], v34 offset:16896
	ds_read_b128 v[40:43], v34 offset:16912
	s_waitcnt vmcnt(18) lgkmcnt(2)
	v_pk_fma_f32 v[18:19], v[184:185], v[44:45], v[18:19] op_sel_hi:[1,0,1]
	v_pk_fma_f32 v[20:21], v[186:187], v[44:45], v[20:21] op_sel_hi:[1,0,1]
	v_pk_fma_f32 v[22:23], v[188:189], v[44:45], v[22:23] op_sel:[0,1,0]
	v_pk_fma_f32 v[24:25], v[190:191], v[44:45], v[24:25] op_sel:[0,1,0]
	v_pk_fma_f32 v[26:27], v[184:185], v[46:47], v[26:27] op_sel_hi:[1,0,1]
	v_pk_fma_f32 v[28:29], v[186:187], v[46:47], v[28:29] op_sel_hi:[1,0,1]
	v_pk_fma_f32 v[6:7], v[188:189], v[46:47], v[6:7] op_sel:[0,1,0]
	v_pk_fma_f32 v[8:9], v[190:191], v[46:47], v[8:9] op_sel:[0,1,0]
	v_pk_fma_f32 v[30:31], v[184:185], v[48:49], v[30:31] op_sel_hi:[1,0,1]
	v_pk_fma_f32 v[32:33], v[186:187], v[48:49], v[32:33] op_sel_hi:[1,0,1]
	v_pk_fma_f32 v[36:37], v[188:189], v[48:49], v[36:37] op_sel:[0,1,0]
	v_pk_fma_f32 v[38:39], v[190:191], v[48:49], v[38:39] op_sel:[0,1,0]
	v_pk_fma_f32 v[10:11], v[184:185], v[50:51], v[10:11] op_sel_hi:[1,0,1]
	v_pk_fma_f32 v[12:13], v[186:187], v[50:51], v[12:13] op_sel_hi:[1,0,1]
	v_pk_fma_f32 v[2:3], v[188:189], v[50:51], v[2:3] op_sel:[0,1,0]
	v_pk_fma_f32 v[4:5], v[190:191], v[50:51], v[4:5] op_sel:[0,1,0]
	global_load_dwordx4 v[184:187], v[86:87], off offset:2048 nt
	global_load_dwordx4 v[188:191], v[86:87], off offset:3072 nt
	v_add_co_u32_e32 v86, vcc, 0x1000, v86
	s_nop 1
	v_addc_co_u32_e32 v87, vcc, 0, v87, vcc
	ds_read_b128 v[44:47], v34 offset:16960
	ds_read_b128 v[48:51], v34 offset:16976
	s_waitcnt vmcnt(18) lgkmcnt(2)
	v_pk_fma_f32 v[18:19], v[192:193], v[14:15], v[18:19] op_sel_hi:[1,0,1]
	v_pk_fma_f32 v[20:21], v[194:195], v[14:15], v[20:21] op_sel_hi:[1,0,1]
	v_pk_fma_f32 v[22:23], v[196:197], v[14:15], v[22:23] op_sel:[0,1,0]
	v_pk_fma_f32 v[24:25], v[198:199], v[14:15], v[24:25] op_sel:[0,1,0]
	v_pk_fma_f32 v[26:27], v[192:193], v[16:17], v[26:27] op_sel_hi:[1,0,1]
	v_pk_fma_f32 v[28:29], v[194:195], v[16:17], v[28:29] op_sel_hi:[1,0,1]
	v_pk_fma_f32 v[6:7], v[196:197], v[16:17], v[6:7] op_sel:[0,1,0]
	v_pk_fma_f32 v[8:9], v[198:199], v[16:17], v[8:9] op_sel:[0,1,0]
	v_pk_fma_f32 v[30:31], v[192:193], v[40:41], v[30:31] op_sel_hi:[1,0,1]
	v_pk_fma_f32 v[32:33], v[194:195], v[40:41], v[32:33] op_sel_hi:[1,0,1]
	v_pk_fma_f32 v[36:37], v[196:197], v[40:41], v[36:37] op_sel:[0,1,0]
	v_pk_fma_f32 v[38:39], v[198:199], v[40:41], v[38:39] op_sel:[0,1,0]
	v_pk_fma_f32 v[10:11], v[192:193], v[42:43], v[10:11] op_sel_hi:[1,0,1]
	v_pk_fma_f32 v[12:13], v[194:195], v[42:43], v[12:13] op_sel_hi:[1,0,1]
	v_pk_fma_f32 v[2:3], v[196:197], v[42:43], v[2:3] op_sel:[0,1,0]
	v_pk_fma_f32 v[4:5], v[198:199], v[42:43], v[4:5] op_sel:[0,1,0]
	global_load_dwordx4 v[192:195], v[86:87], off nt
	global_load_dwordx4 v[196:199], v[86:87], off offset:1024 nt
	ds_read_b128 v[14:17], v34 offset:17024
	ds_read_b128 v[40:43], v34 offset:17040
	s_waitcnt vmcnt(18) lgkmcnt(2)
	v_pk_fma_f32 v[18:19], v[200:201], v[44:45], v[18:19] op_sel_hi:[1,0,1]
	v_pk_fma_f32 v[20:21], v[202:203], v[44:45], v[20:21] op_sel_hi:[1,0,1]
	v_pk_fma_f32 v[22:23], v[204:205], v[44:45], v[22:23] op_sel:[0,1,0]
	v_pk_fma_f32 v[24:25], v[206:207], v[44:45], v[24:25] op_sel:[0,1,0]
	v_pk_fma_f32 v[26:27], v[200:201], v[46:47], v[26:27] op_sel_hi:[1,0,1]
	v_pk_fma_f32 v[28:29], v[202:203], v[46:47], v[28:29] op_sel_hi:[1,0,1]
	v_pk_fma_f32 v[6:7], v[204:205], v[46:47], v[6:7] op_sel:[0,1,0]
	v_pk_fma_f32 v[8:9], v[206:207], v[46:47], v[8:9] op_sel:[0,1,0]
	v_pk_fma_f32 v[30:31], v[200:201], v[48:49], v[30:31] op_sel_hi:[1,0,1]
	v_pk_fma_f32 v[32:33], v[202:203], v[48:49], v[32:33] op_sel_hi:[1,0,1]
	v_pk_fma_f32 v[36:37], v[204:205], v[48:49], v[36:37] op_sel:[0,1,0]
	v_pk_fma_f32 v[38:39], v[206:207], v[48:49], v[38:39] op_sel:[0,1,0]
	v_pk_fma_f32 v[10:11], v[200:201], v[50:51], v[10:11] op_sel_hi:[1,0,1]
	v_pk_fma_f32 v[12:13], v[202:203], v[50:51], v[12:13] op_sel_hi:[1,0,1]
	v_pk_fma_f32 v[2:3], v[204:205], v[50:51], v[2:3] op_sel:[0,1,0]
	v_pk_fma_f32 v[4:5], v[206:207], v[50:51], v[4:5] op_sel:[0,1,0]
	global_load_dwordx4 v[200:203], v[86:87], off offset:2048 nt
	global_load_dwordx4 v[204:207], v[86:87], off offset:3072 nt
	v_add_co_u32_e32 v86, vcc, 0x1000, v86
	s_nop 1
	v_addc_co_u32_e32 v87, vcc, 0, v87, vcc
	ds_read_b128 v[44:47], v34 offset:17088
	ds_read_b128 v[48:51], v34 offset:17104
	s_waitcnt vmcnt(18) lgkmcnt(2)
; #define DEC_LOADV(dst, i0) do { asm volatile("" ::: "memory"); _Pragma("unroll") for (int u = 0; u < 4; ++u) { const float* vr = cv + rbase + (size_t)((i0) + u) * 512; dst[u][0] = __builtin_nontemporal_load((const f32x4*)(vr + 4 * lane)); dst[u][1] = __builtin_nontemporal_load((const f32x4*)(vr + 256 + 4 * lane)); } } while (0)
; __device__ __forceinline__ void decode_item(Frame& F, const Args& a, int l, int item, unsigned char* ws) {
;     ...
;         DEC_LOADV(va, 0); DEC_LOADV(vb, 4); DEC_ACC(va, 0); DEC_LOADV(va, 8); DEC_ACC(vb, 4); DEC_LOADV(vb, 12); DEC_ACC(va, 8); DEC_LOADV(va, 16); DEC_ACC(vb, 12); DEC_LOADV(vb, 20); DEC_ACC(va, 16); DEC_LOADV(va, 24); DEC_ACC(vb, 20); DEC_LOADV(vb, 28); DEC_ACC(va, 24); DEC_ACC(vb, 28);
	v_pk_fma_f32 v[18:19], v[52:53], v[14:15], v[18:19] op_sel_hi:[1,0,1]
	v_pk_fma_f32 v[20:21], v[54:55], v[14:15], v[20:21] op_sel_hi:[1,0,1]
	v_pk_fma_f32 v[22:23], v[56:57], v[14:15], v[22:23] op_sel:[0,1,0]
	v_pk_fma_f32 v[24:25], v[58:59], v[14:15], v[24:25] op_sel:[0,1,0]
	v_pk_fma_f32 v[26:27], v[52:53], v[16:17], v[26:27] op_sel_hi:[1,0,1]
	v_pk_fma_f32 v[28:29], v[54:55], v[16:17], v[28:29] op_sel_hi:[1,0,1]
	v_pk_fma_f32 v[6:7], v[56:57], v[16:17], v[6:7] op_sel:[0,1,0]
	v_pk_fma_f32 v[8:9], v[58:59], v[16:17], v[8:9] op_sel:[0,1,0]
	v_pk_fma_f32 v[30:31], v[52:53], v[40:41], v[30:31] op_sel_hi:[1,0,1]
	v_pk_fma_f32 v[32:33], v[54:55], v[40:41], v[32:33] op_sel_hi:[1,0,1]
	v_pk_fma_f32 v[36:37], v[56:57], v[40:41], v[36:37] op_sel:[0,1,0]
	v_pk_fma_f32 v[38:39], v[58:59], v[40:41], v[38:39] op_sel:[0,1,0]
	v_pk_fma_f32 v[10:11], v[52:53], v[42:43], v[10:11] op_sel_hi:[1,0,1]
	v_pk_fma_f32 v[12:13], v[54:55], v[42:43], v[12:13] op_sel_hi:[1,0,1]
	v_pk_fma_f32 v[2:3], v[56:57], v[42:43], v[2:3] op_sel:[0,1,0]
	v_pk_fma_f32 v[4:5], v[58:59], v[42:43], v[4:5] op_sel:[0,1,0]
	global_load_dwordx4 v[52:55], v[86:87], off nt
	global_load_dwordx4 v[56:59], v[86:87], off offset:1024 nt
	ds_read_b128 v[14:17], v34 offset:17152
	ds_read_b128 v[40:43], v34 offset:17168
	s_waitcnt vmcnt(18) lgkmcnt(2)
	v_pk_fma_f32 v[18:19], v[60:61], v[44:45], v[18:19] op_sel_hi:[1,0,1]
	v_pk_fma_f32 v[20:21], v[62:63], v[44:45], v[20:21] op_sel_hi:[1,0,1]
	v_pk_fma_f32 v[22:23], v[64:65], v[44:45], v[22:23] op_sel:[0,1,0]
	v_pk_fma_f32 v[24:25], v[66:67], v[44:45], v[24:25] op_sel:[0,1,0]
	v_pk_fma_f32 v[26:27], v[60:61], v[46:47], v[26:27] op_sel_hi:[1,0,1]
	v_pk_fma_f32 v[28:29], v[62:63], v[46:47], v[28:29] op_sel_hi:[1,0,1]
	v_pk_fma_f32 v[6:7], v[64:65], v[46:47], v[6:7] op_sel:[0,1,0]
	v_pk_fma_f32 v[8:9], v[66:67], v[46:47], v[8:9] op_sel:[0,1,0]
	v_pk_fma_f32 v[30:31], v[60:61], v[48:49], v[30:31] op_sel_hi:[1,0,1]
	v_pk_fma_f32 v[32:33], v[62:63], v[48:49], v[32:33] op_sel_hi:[1,0,1]
	v_pk_fma_f32 v[36:37], v[64:65], v[48:49], v[36:37] op_sel:[0,1,0]
	v_pk_fma_f32 v[38:39], v[66:67], v[48:49], v[38:39] op_sel:[0,1,0]
	v_pk_fma_f32 v[10:11], v[60:61], v[50:51], v[10:11] op_sel_hi:[1,0,1]
	v_pk_fma_f32 v[12:13], v[62:63], v[50:51], v[12:13] op_sel_hi:[1,0,1]
	v_pk_fma_f32 v[2:3], v[64:65], v[50:51], v[2:3] op_sel:[0,1,0]
	v_pk_fma_f32 v[4:5], v[66:67], v[50:51], v[4:5] op_sel:[0,1,0]
	global_load_dwordx4 v[60:63], v[86:87], off offset:2048 nt
	global_load_dwordx4 v[64:67], v[86:87], off offset:3072 nt
	v_add_co_u32_e32 v86, vcc, 0x1000, v86
	s_nop 1
	v_addc_co_u32_e32 v87, vcc, 0, v87, vcc
	ds_read_b128 v[44:47], v34 offset:17216
	ds_read_b128 v[48:51], v34 offset:17232
	s_waitcnt vmcnt(18) lgkmcnt(2)
	v_pk_fma_f32 v[18:19], v[68:69], v[14:15], v[18:19] op_sel_hi:[1,0,1]
	v_pk_fma_f32 v[20:21], v[70:71], v[14:15], v[20:21] op_sel_hi:[1,0,1]
	v_pk_fma_f32 v[22:23], v[72:73], v[14:15], v[22:23] op_sel:[0,1,0]
	v_pk_fma_f32 v[24:25], v[74:75], v[14:15], v[24:25] op_sel:[0,1,0]
	v_pk_fma_f32 v[26:27], v[68:69], v[16:17], v[26:27] op_sel_hi:[1,0,1]
	v_pk_fma_f32 v[28:29], v[70:71], v[16:17], v[28:29] op_sel_hi:[1,0,1]
	v_pk_fma_f32 v[6:7], v[72:73], v[16:17], v[6:7] op_sel:[0,1,0]
	v_pk_fma_f32 v[8:9], v[74:75], v[16:17], v[8:9] op_sel:[0,1,0]
	v_pk_fma_f32 v[30:31], v[68:69], v[40:41], v[30:31] op_sel_hi:[1,0,1]
	v_pk_fma_f32 v[32:33], v[70:71], v[40:41], v[32:33] op_sel_hi:[1,0,1]
	v_pk_fma_f32 v[36:37], v[72:73], v[40:41], v[36:37] op_sel:[0,1,0]
	v_pk_fma_f32 v[38:39], v[74:75], v[40:41], v[38:39] op_sel:[0,1,0]
	v_pk_fma_f32 v[10:11], v[68:69], v[42:43], v[10:11] op_sel_hi:[1,0,1]
	v_pk_fma_f32 v[12:13], v[70:71], v[42:43], v[12:13] op_sel_hi:[1,0,1]
	v_pk_fma_f32 v[2:3], v[72:73], v[42:43], v[2:3] op_sel:[0,1,0]
	v_pk_fma_f32 v[4:5], v[74:75], v[42:43], v[4:5] op_sel:[0,1,0]
	global_load_dwordx4 v[68:71], v[86:87], off nt
	global_load_dwordx4 v[72:75], v[86:87], off offset:1024 nt
	ds_read_b128 v[14:17], v34 offset:17280
	ds_read_b128 v[40:43], v34 offset:17296
	s_waitcnt vmcnt(18) lgkmcnt(2)
	v_pk_fma_f32 v[18:19], v[76:77], v[44:45], v[18:19] op_sel_hi:[1,0,1]
	v_pk_fma_f32 v[20:21], v[78:79], v[44:45], v[20:21] op_sel_hi:[1,0,1]
	v_pk_fma_f32 v[22:23], v[80:81], v[44:45], v[22:23] op_sel:[0,1,0]
	v_pk_fma_f32 v[24:25], v[82:83], v[44:45], v[24:25] op_sel:[0,1,0]
	v_pk_fma_f32 v[26:27], v[76:77], v[46:47], v[26:27] op_sel_hi:[1,0,1]
	v_pk_fma_f32 v[28:29], v[78:79], v[46:47], v[28:29] op_sel_hi:[1,0,1]
	v_pk_fma_f32 v[6:7], v[80:81], v[46:47], v[6:7] op_sel:[0,1,0]
	v_pk_fma_f32 v[8:9], v[82:83], v[46:47], v[8:9] op_sel:[0,1,0]
	v_pk_fma_f32 v[30:31], v[76:77], v[48:49], v[30:31] op_sel_hi:[1,0,1]
	v_pk_fma_f32 v[32:33], v[78:79], v[48:49], v[32:33] op_sel_hi:[1,0,1]
	v_pk_fma_f32 v[36:37], v[80:81], v[48:49], v[36:37] op_sel:[0,1,0]
	v_pk_fma_f32 v[38:39], v[82:83], v[48:49], v[38:39] op_sel:[0,1,0]
	v_pk_fma_f32 v[10:11], v[76:77], v[50:51], v[10:11] op_sel_hi:[1,0,1]
	v_pk_fma_f32 v[12:13], v[78:79], v[50:51], v[12:13] op_sel_hi:[1,0,1]
	v_pk_fma_f32 v[2:3], v[80:81], v[50:51], v[2:3] op_sel:[0,1,0]
	v_pk_fma_f32 v[4:5], v[82:83], v[50:51], v[4:5] op_sel:[0,1,0]
	global_load_dwordx4 v[76:79], v[86:87], off offset:2048 nt
	global_load_dwordx4 v[80:83], v[86:87], off offset:3072 nt
	v_add_co_u32_e32 v86, vcc, 0x1000, v86
	s_nop 1
	v_addc_co_u32_e32 v87, vcc, 0, v87, vcc
	ds_read_b128 v[44:47], v34 offset:17344
	ds_read_b128 v[48:51], v34 offset:17360
	s_waitcnt vmcnt(18) lgkmcnt(2)
; #define DEC_LOADV(dst, i0) do { asm volatile("" ::: "memory"); _Pragma("unroll") for (int u = 0; u < 4; ++u) { const float* vr = cv + rbase + (size_t)((i0) + u) * 512; dst[u][0] = __builtin_nontemporal_load((const f32x4*)(vr + 4 * lane)); dst[u][1] = __builtin_nontemporal_load((const f32x4*)(vr + 256 + 4 * lane)); } } while (0)
; __device__ __forceinline__ void decode_item(Frame& F, const Args& a, int l, int item, unsigned char* ws) {
;     ...
;         DEC_LOADV(va, 0); DEC_LOADV(vb, 4); DEC_ACC(va, 0); DEC_LOADV(va, 8); DEC_ACC(vb, 4); DEC_LOADV(vb, 12); DEC_ACC(va, 8); DEC_LOADV(va, 16); DEC_ACC(vb, 12); DEC_LOADV(vb, 20); DEC_ACC(va, 16); DEC_LOADV(va, 24); DEC_ACC(vb, 20); DEC_LOADV(vb, 28); DEC_ACC(va, 24); DEC_ACC(vb, 28);
	v_pk_fma_f32 v[18:19], v[88:89], v[14:15], v[18:19] op_sel_hi:[1,0,1]
	v_pk_fma_f32 v[20:21], v[90:91], v[14:15], v[20:21] op_sel_hi:[1,0,1]
	v_pk_fma_f32 v[22:23], v[92:93], v[14:15], v[22:23] op_sel:[0,1,0]
	v_pk_fma_f32 v[24:25], v[94:95], v[14:15], v[24:25] op_sel:[0,1,0]
	v_pk_fma_f32 v[26:27], v[88:89], v[16:17], v[26:27] op_sel_hi:[1,0,1]
	v_pk_fma_f32 v[28:29], v[90:91], v[16:17], v[28:29] op_sel_hi:[1,0,1]
	v_pk_fma_f32 v[6:7], v[92:93], v[16:17], v[6:7] op_sel:[0,1,0]
	v_pk_fma_f32 v[8:9], v[94:95], v[16:17], v[8:9] op_sel:[0,1,0]
	v_pk_fma_f32 v[30:31], v[88:89], v[40:41], v[30:31] op_sel_hi:[1,0,1]
	v_pk_fma_f32 v[32:33], v[90:91], v[40:41], v[32:33] op_sel_hi:[1,0,1]
	v_pk_fma_f32 v[36:37], v[92:93], v[40:41], v[36:37] op_sel:[0,1,0]
	v_pk_fma_f32 v[38:39], v[94:95], v[40:41], v[38:39] op_sel:[0,1,0]
	v_pk_fma_f32 v[10:11], v[88:89], v[42:43], v[10:11] op_sel_hi:[1,0,1]
	v_pk_fma_f32 v[12:13], v[90:91], v[42:43], v[12:13] op_sel_hi:[1,0,1]
	v_pk_fma_f32 v[2:3], v[92:93], v[42:43], v[2:3] op_sel:[0,1,0]
	v_pk_fma_f32 v[4:5], v[94:95], v[42:43], v[4:5] op_sel:[0,1,0]
	global_load_dwordx4 v[88:91], v[86:87], off nt
	global_load_dwordx4 v[92:95], v[86:87], off offset:1024 nt
	ds_read_b128 v[14:17], v34 offset:17408
	ds_read_b128 v[40:43], v34 offset:17424
	s_waitcnt vmcnt(18) lgkmcnt(2)
	v_pk_fma_f32 v[18:19], v[96:97], v[44:45], v[18:19] op_sel_hi:[1,0,1]
	v_pk_fma_f32 v[20:21], v[98:99], v[44:45], v[20:21] op_sel_hi:[1,0,1]
	v_pk_fma_f32 v[22:23], v[100:101], v[44:45], v[22:23] op_sel:[0,1,0]
	v_pk_fma_f32 v[24:25], v[102:103], v[44:45], v[24:25] op_sel:[0,1,0]
	v_pk_fma_f32 v[26:27], v[96:97], v[46:47], v[26:27] op_sel_hi:[1,0,1]
	v_pk_fma_f32 v[28:29], v[98:99], v[46:47], v[28:29] op_sel_hi:[1,0,1]
	v_pk_fma_f32 v[6:7], v[100:101], v[46:47], v[6:7] op_sel:[0,1,0]
	v_pk_fma_f32 v[8:9], v[102:103], v[46:47], v[8:9] op_sel:[0,1,0]
	v_pk_fma_f32 v[30:31], v[96:97], v[48:49], v[30:31] op_sel_hi:[1,0,1]
	v_pk_fma_f32 v[32:33], v[98:99], v[48:49], v[32:33] op_sel_hi:[1,0,1]
	v_pk_fma_f32 v[36:37], v[100:101], v[48:49], v[36:37] op_sel:[0,1,0]
	v_pk_fma_f32 v[38:39], v[102:103], v[48:49], v[38:39] op_sel:[0,1,0]
	v_pk_fma_f32 v[10:11], v[96:97], v[50:51], v[10:11] op_sel_hi:[1,0,1]
	v_pk_fma_f32 v[12:13], v[98:99], v[50:51], v[12:13] op_sel_hi:[1,0,1]
	v_pk_fma_f32 v[2:3], v[100:101], v[50:51], v[2:3] op_sel:[0,1,0]
	v_pk_fma_f32 v[4:5], v[102:103], v[50:51], v[4:5] op_sel:[0,1,0]
	global_load_dwordx4 v[96:99], v[86:87], off offset:2048 nt
	global_load_dwordx4 v[100:103], v[86:87], off offset:3072 nt
	v_add_co_u32_e32 v86, vcc, 0x1000, v86
	s_nop 1
	v_addc_co_u32_e32 v87, vcc, 0, v87, vcc
	ds_read_b128 v[44:47], v34 offset:17472
	ds_read_b128 v[48:51], v34 offset:17488
	s_waitcnt vmcnt(18) lgkmcnt(2)
	v_pk_fma_f32 v[18:19], v[104:105], v[14:15], v[18:19] op_sel_hi:[1,0,1]
	v_pk_fma_f32 v[20:21], v[106:107], v[14:15], v[20:21] op_sel_hi:[1,0,1]
	v_pk_fma_f32 v[22:23], v[108:109], v[14:15], v[22:23] op_sel:[0,1,0]
	v_pk_fma_f32 v[24:25], v[110:111], v[14:15], v[24:25] op_sel:[0,1,0]
	v_pk_fma_f32 v[26:27], v[104:105], v[16:17], v[26:27] op_sel_hi:[1,0,1]
	v_pk_fma_f32 v[28:29], v[106:107], v[16:17], v[28:29] op_sel_hi:[1,0,1]
	v_pk_fma_f32 v[6:7], v[108:109], v[16:17], v[6:7] op_sel:[0,1,0]
	v_pk_fma_f32 v[8:9], v[110:111], v[16:17], v[8:9] op_sel:[0,1,0]
	v_pk_fma_f32 v[30:31], v[104:105], v[40:41], v[30:31] op_sel_hi:[1,0,1]
	v_pk_fma_f32 v[32:33], v[106:107], v[40:41], v[32:33] op_sel_hi:[1,0,1]
	v_pk_fma_f32 v[36:37], v[108:109], v[40:41], v[36:37] op_sel:[0,1,0]
	v_pk_fma_f32 v[38:39], v[110:111], v[40:41], v[38:39] op_sel:[0,1,0]
	v_pk_fma_f32 v[10:11], v[104:105], v[42:43], v[10:11] op_sel_hi:[1,0,1]
	v_pk_fma_f32 v[12:13], v[106:107], v[42:43], v[12:13] op_sel_hi:[1,0,1]
	v_pk_fma_f32 v[2:3], v[108:109], v[42:43], v[2:3] op_sel:[0,1,0]
	v_pk_fma_f32 v[4:5], v[110:111], v[42:43], v[4:5] op_sel:[0,1,0]
	global_load_dwordx4 v[104:107], v[86:87], off nt
	global_load_dwordx4 v[108:111], v[86:87], off offset:1024 nt
	ds_read_b128 v[14:17], v34 offset:17536
	ds_read_b128 v[40:43], v34 offset:17552
	s_waitcnt vmcnt(18) lgkmcnt(2)
	v_pk_fma_f32 v[18:19], v[184:185], v[44:45], v[18:19] op_sel_hi:[1,0,1]
	v_pk_fma_f32 v[20:21], v[186:187], v[44:45], v[20:21] op_sel_hi:[1,0,1]
	v_pk_fma_f32 v[22:23], v[188:189], v[44:45], v[22:23] op_sel:[0,1,0]
	v_pk_fma_f32 v[24:25], v[190:191], v[44:45], v[24:25] op_sel:[0,1,0]
	v_pk_fma_f32 v[26:27], v[184:185], v[46:47], v[26:27] op_sel_hi:[1,0,1]
	v_pk_fma_f32 v[28:29], v[186:187], v[46:47], v[28:29] op_sel_hi:[1,0,1]
	v_pk_fma_f32 v[6:7], v[188:189], v[46:47], v[6:7] op_sel:[0,1,0]
	v_pk_fma_f32 v[8:9], v[190:191], v[46:47], v[8:9] op_sel:[0,1,0]
	v_pk_fma_f32 v[30:31], v[184:185], v[48:49], v[30:31] op_sel_hi:[1,0,1]
	v_pk_fma_f32 v[32:33], v[186:187], v[48:49], v[32:33] op_sel_hi:[1,0,1]
	v_pk_fma_f32 v[36:37], v[188:189], v[48:49], v[36:37] op_sel:[0,1,0]
	v_pk_fma_f32 v[38:39], v[190:191], v[48:49], v[38:39] op_sel:[0,1,0]
	v_pk_fma_f32 v[10:11], v[184:185], v[50:51], v[10:11] op_sel_hi:[1,0,1]
	v_pk_fma_f32 v[12:13], v[186:187], v[50:51], v[12:13] op_sel_hi:[1,0,1]
	v_pk_fma_f32 v[2:3], v[188:189], v[50:51], v[2:3] op_sel:[0,1,0]
	v_pk_fma_f32 v[4:5], v[190:191], v[50:51], v[4:5] op_sel:[0,1,0]
	global_load_dwordx4 v[184:187], v[86:87], off offset:2048 nt
	global_load_dwordx4 v[188:191], v[86:87], off offset:3072 nt
	v_add_co_u32_e32 v86, vcc, 0x1000, v86
	s_nop 1
	v_addc_co_u32_e32 v87, vcc, 0, v87, vcc
	ds_read_b128 v[44:47], v34 offset:17600
	ds_read_b128 v[48:51], v34 offset:17616
	s_waitcnt vmcnt(18) lgkmcnt(2)
; #define DEC_LOADV(dst, i0) do { asm volatile("" ::: "memory"); _Pragma("unroll") for (int u = 0; u < 4; ++u) { const float* vr = cv + rbase + (size_t)((i0) + u) * 512; dst[u][0] = __builtin_nontemporal_load((const f32x4*)(vr + 4 * lane)); dst[u][1] = __builtin_nontemporal_load((const f32x4*)(vr + 256 + 4 * lane)); } } while (0)
; __device__ __forceinline__ void decode_item(Frame& F, const Args& a, int l, int item, unsigned char* ws) {
;     ...
;         DEC_LOADV(va, 0); DEC_LOADV(vb, 4); DEC_ACC(va, 0); DEC_LOADV(va, 8); DEC_ACC(vb, 4); DEC_LOADV(vb, 12); DEC_ACC(va, 8); DEC_LOADV(va, 16); DEC_ACC(vb, 12); DEC_LOADV(vb, 20); DEC_ACC(va, 16); DEC_LOADV(va, 24); DEC_ACC(vb, 20); DEC_LOADV(vb, 28); DEC_ACC(va, 24); DEC_ACC(vb, 28);
	v_pk_fma_f32 v[18:19], v[192:193], v[14:15], v[18:19] op_sel_hi:[1,0,1]
	v_pk_fma_f32 v[20:21], v[194:195], v[14:15], v[20:21] op_sel_hi:[1,0,1]
	v_pk_fma_f32 v[22:23], v[196:197], v[14:15], v[22:23] op_sel:[0,1,0]
	v_pk_fma_f32 v[24:25], v[198:199], v[14:15], v[24:25] op_sel:[0,1,0]
	v_pk_fma_f32 v[26:27], v[192:193], v[16:17], v[26:27] op_sel_hi:[1,0,1]
	v_pk_fma_f32 v[28:29], v[194:195], v[16:17], v[28:29] op_sel_hi:[1,0,1]
	v_pk_fma_f32 v[6:7], v[196:197], v[16:17], v[6:7] op_sel:[0,1,0]
	v_pk_fma_f32 v[8:9], v[198:199], v[16:17], v[8:9] op_sel:[0,1,0]
	v_pk_fma_f32 v[30:31], v[192:193], v[40:41], v[30:31] op_sel_hi:[1,0,1]
	v_pk_fma_f32 v[32:33], v[194:195], v[40:41], v[32:33] op_sel_hi:[1,0,1]
	v_pk_fma_f32 v[36:37], v[196:197], v[40:41], v[36:37] op_sel:[0,1,0]
	v_pk_fma_f32 v[38:39], v[198:199], v[40:41], v[38:39] op_sel:[0,1,0]
	v_pk_fma_f32 v[10:11], v[192:193], v[42:43], v[10:11] op_sel_hi:[1,0,1]
	v_pk_fma_f32 v[12:13], v[194:195], v[42:43], v[12:13] op_sel_hi:[1,0,1]
	v_pk_fma_f32 v[2:3], v[196:197], v[42:43], v[2:3] op_sel:[0,1,0]
	v_pk_fma_f32 v[4:5], v[198:199], v[42:43], v[4:5] op_sel:[0,1,0]
	global_load_dwordx4 v[192:195], v[86:87], off nt
	global_load_dwordx4 v[196:199], v[86:87], off offset:1024 nt
	ds_read_b128 v[14:17], v34 offset:17664
	ds_read_b128 v[40:43], v34 offset:17680
	s_waitcnt vmcnt(18) lgkmcnt(2)
	v_pk_fma_f32 v[18:19], v[200:201], v[44:45], v[18:19] op_sel_hi:[1,0,1]
	v_pk_fma_f32 v[20:21], v[202:203], v[44:45], v[20:21] op_sel_hi:[1,0,1]
	v_pk_fma_f32 v[22:23], v[204:205], v[44:45], v[22:23] op_sel:[0,1,0]
	v_pk_fma_f32 v[24:25], v[206:207], v[44:45], v[24:25] op_sel:[0,1,0]
	v_pk_fma_f32 v[26:27], v[200:201], v[46:47], v[26:27] op_sel_hi:[1,0,1]
	v_pk_fma_f32 v[28:29], v[202:203], v[46:47], v[28:29] op_sel_hi:[1,0,1]
	v_pk_fma_f32 v[6:7], v[204:205], v[46:47], v[6:7] op_sel:[0,1,0]
	v_pk_fma_f32 v[8:9], v[206:207], v[46:47], v[8:9] op_sel:[0,1,0]
	v_pk_fma_f32 v[30:31], v[200:201], v[48:49], v[30:31] op_sel_hi:[1,0,1]
	v_pk_fma_f32 v[32:33], v[202:203], v[48:49], v[32:33] op_sel_hi:[1,0,1]
	v_pk_fma_f32 v[36:37], v[204:205], v[48:49], v[36:37] op_sel:[0,1,0]
	v_pk_fma_f32 v[38:39], v[206:207], v[48:49], v[38:39] op_sel:[0,1,0]
	v_pk_fma_f32 v[10:11], v[200:201], v[50:51], v[10:11] op_sel_hi:[1,0,1]
	v_pk_fma_f32 v[12:13], v[202:203], v[50:51], v[12:13] op_sel_hi:[1,0,1]
	v_pk_fma_f32 v[2:3], v[204:205], v[50:51], v[2:3] op_sel:[0,1,0]
	v_pk_fma_f32 v[4:5], v[206:207], v[50:51], v[4:5] op_sel:[0,1,0]
	global_load_dwordx4 v[200:203], v[86:87], off offset:2048 nt
	global_load_dwordx4 v[204:207], v[86:87], off offset:3072 nt
	v_add_co_u32_e32 v86, vcc, 0x1000, v86
	s_nop 1
	v_addc_co_u32_e32 v87, vcc, 0, v87, vcc
	ds_read_b128 v[44:47], v34 offset:17728
	ds_read_b128 v[48:51], v34 offset:17744
	s_waitcnt vmcnt(18) lgkmcnt(2)
	v_pk_fma_f32 v[18:19], v[52:53], v[14:15], v[18:19] op_sel_hi:[1,0,1]
	v_pk_fma_f32 v[20:21], v[54:55], v[14:15], v[20:21] op_sel_hi:[1,0,1]
	v_pk_fma_f32 v[22:23], v[56:57], v[14:15], v[22:23] op_sel:[0,1,0]
	v_pk_fma_f32 v[24:25], v[58:59], v[14:15], v[24:25] op_sel:[0,1,0]
	v_pk_fma_f32 v[26:27], v[52:53], v[16:17], v[26:27] op_sel_hi:[1,0,1]
	v_pk_fma_f32 v[28:29], v[54:55], v[16:17], v[28:29] op_sel_hi:[1,0,1]
	v_pk_fma_f32 v[6:7], v[56:57], v[16:17], v[6:7] op_sel:[0,1,0]
	v_pk_fma_f32 v[8:9], v[58:59], v[16:17], v[8:9] op_sel:[0,1,0]
	v_pk_fma_f32 v[30:31], v[52:53], v[40:41], v[30:31] op_sel_hi:[1,0,1]
	v_pk_fma_f32 v[32:33], v[54:55], v[40:41], v[32:33] op_sel_hi:[1,0,1]
	v_pk_fma_f32 v[36:37], v[56:57], v[40:41], v[36:37] op_sel:[0,1,0]
	v_pk_fma_f32 v[38:39], v[58:59], v[40:41], v[38:39] op_sel:[0,1,0]
	v_pk_fma_f32 v[10:11], v[52:53], v[42:43], v[10:11] op_sel_hi:[1,0,1]
	v_pk_fma_f32 v[12:13], v[54:55], v[42:43], v[12:13] op_sel_hi:[1,0,1]
	v_pk_fma_f32 v[2:3], v[56:57], v[42:43], v[2:3] op_sel:[0,1,0]
	v_pk_fma_f32 v[4:5], v[58:59], v[42:43], v[4:5] op_sel:[0,1,0]
	global_load_dwordx4 v[52:55], v[86:87], off nt
	global_load_dwordx4 v[56:59], v[86:87], off offset:1024 nt
	ds_read_b128 v[14:17], v34 offset:17792
	ds_read_b128 v[40:43], v34 offset:17808
	s_waitcnt vmcnt(18) lgkmcnt(2)
	v_pk_fma_f32 v[18:19], v[60:61], v[44:45], v[18:19] op_sel_hi:[1,0,1]
	v_pk_fma_f32 v[20:21], v[62:63], v[44:45], v[20:21] op_sel_hi:[1,0,1]
	v_pk_fma_f32 v[22:23], v[64:65], v[44:45], v[22:23] op_sel:[0,1,0]
	v_pk_fma_f32 v[24:25], v[66:67], v[44:45], v[24:25] op_sel:[0,1,0]
	v_pk_fma_f32 v[26:27], v[60:61], v[46:47], v[26:27] op_sel_hi:[1,0,1]
	v_pk_fma_f32 v[28:29], v[62:63], v[46:47], v[28:29] op_sel_hi:[1,0,1]
	v_pk_fma_f32 v[6:7], v[64:65], v[46:47], v[6:7] op_sel:[0,1,0]
	v_pk_fma_f32 v[8:9], v[66:67], v[46:47], v[8:9] op_sel:[0,1,0]
	v_pk_fma_f32 v[30:31], v[60:61], v[48:49], v[30:31] op_sel_hi:[1,0,1]
	v_pk_fma_f32 v[32:33], v[62:63], v[48:49], v[32:33] op_sel_hi:[1,0,1]
	v_pk_fma_f32 v[36:37], v[64:65], v[48:49], v[36:37] op_sel:[0,1,0]
	v_pk_fma_f32 v[38:39], v[66:67], v[48:49], v[38:39] op_sel:[0,1,0]
	v_pk_fma_f32 v[10:11], v[60:61], v[50:51], v[10:11] op_sel_hi:[1,0,1]
	v_pk_fma_f32 v[12:13], v[62:63], v[50:51], v[12:13] op_sel_hi:[1,0,1]
	v_pk_fma_f32 v[2:3], v[64:65], v[50:51], v[2:3] op_sel:[0,1,0]
	v_pk_fma_f32 v[4:5], v[66:67], v[50:51], v[4:5] op_sel:[0,1,0]
	global_load_dwordx4 v[60:63], v[86:87], off offset:2048 nt
	global_load_dwordx4 v[64:67], v[86:87], off offset:3072 nt
	v_add_co_u32_e32 v86, vcc, 0x1000, v86
	s_nop 1
	v_addc_co_u32_e32 v87, vcc, 0, v87, vcc
	ds_read_b128 v[44:47], v34 offset:17856
	ds_read_b128 v[48:51], v34 offset:17872
	s_waitcnt vmcnt(18) lgkmcnt(2)
; #define DEC_LOADV(dst, i0) do { asm volatile("" ::: "memory"); _Pragma("unroll") for (int u = 0; u < 4; ++u) { const float* vr = cv + rbase + (size_t)((i0) + u) * 512; dst[u][0] = __builtin_nontemporal_load((const f32x4*)(vr + 4 * lane)); dst[u][1] = __builtin_nontemporal_load((const f32x4*)(vr + 256 + 4 * lane)); } } while (0)
; __device__ __forceinline__ void decode_item(Frame& F, const Args& a, int l, int item, unsigned char* ws) {
;     ...
;         DEC_LOADV(va, 0); DEC_LOADV(vb, 4); DEC_ACC(va, 0); DEC_LOADV(va, 8); DEC_ACC(vb, 4); DEC_LOADV(vb, 12); DEC_ACC(va, 8); DEC_LOADV(va, 16); DEC_ACC(vb, 12); DEC_LOADV(vb, 20); DEC_ACC(va, 16); DEC_LOADV(va, 24); DEC_ACC(vb, 20); DEC_LOADV(vb, 28); DEC_ACC(va, 24); DEC_ACC(vb, 28);
	v_pk_fma_f32 v[18:19], v[68:69], v[14:15], v[18:19] op_sel_hi:[1,0,1]
	v_pk_fma_f32 v[20:21], v[70:71], v[14:15], v[20:21] op_sel_hi:[1,0,1]
	v_pk_fma_f32 v[22:23], v[72:73], v[14:15], v[22:23] op_sel:[0,1,0]
	v_pk_fma_f32 v[24:25], v[74:75], v[14:15], v[24:25] op_sel:[0,1,0]
	v_pk_fma_f32 v[26:27], v[68:69], v[16:17], v[26:27] op_sel_hi:[1,0,1]
	v_pk_fma_f32 v[28:29], v[70:71], v[16:17], v[28:29] op_sel_hi:[1,0,1]
	v_pk_fma_f32 v[6:7], v[72:73], v[16:17], v[6:7] op_sel:[0,1,0]
	v_pk_fma_f32 v[8:9], v[74:75], v[16:17], v[8:9] op_sel:[0,1,0]
	v_pk_fma_f32 v[30:31], v[68:69], v[40:41], v[30:31] op_sel_hi:[1,0,1]
	v_pk_fma_f32 v[32:33], v[70:71], v[40:41], v[32:33] op_sel_hi:[1,0,1]
	v_pk_fma_f32 v[36:37], v[72:73], v[40:41], v[36:37] op_sel:[0,1,0]
	v_pk_fma_f32 v[38:39], v[74:75], v[40:41], v[38:39] op_sel:[0,1,0]
	v_pk_fma_f32 v[10:11], v[68:69], v[42:43], v[10:11] op_sel_hi:[1,0,1]
	v_pk_fma_f32 v[12:13], v[70:71], v[42:43], v[12:13] op_sel_hi:[1,0,1]
	v_pk_fma_f32 v[2:3], v[72:73], v[42:43], v[2:3] op_sel:[0,1,0]
	v_pk_fma_f32 v[4:5], v[74:75], v[42:43], v[4:5] op_sel:[0,1,0]
	ds_read_b128 v[14:17], v34 offset:17920
	ds_read_b128 v[40:43], v34 offset:17936
	s_waitcnt vmcnt(16) lgkmcnt(2)
	v_pk_fma_f32 v[18:19], v[76:77], v[44:45], v[18:19] op_sel_hi:[1,0,1]
	v_pk_fma_f32 v[20:21], v[78:79], v[44:45], v[20:21] op_sel_hi:[1,0,1]
	v_pk_fma_f32 v[22:23], v[80:81], v[44:45], v[22:23] op_sel:[0,1,0]
	v_pk_fma_f32 v[24:25], v[82:83], v[44:45], v[24:25] op_sel:[0,1,0]
	v_pk_fma_f32 v[26:27], v[76:77], v[46:47], v[26:27] op_sel_hi:[1,0,1]
	v_pk_fma_f32 v[28:29], v[78:79], v[46:47], v[28:29] op_sel_hi:[1,0,1]
	v_pk_fma_f32 v[6:7], v[80:81], v[46:47], v[6:7] op_sel:[0,1,0]
	v_pk_fma_f32 v[8:9], v[82:83], v[46:47], v[8:9] op_sel:[0,1,0]
	v_pk_fma_f32 v[30:31], v[76:77], v[48:49], v[30:31] op_sel_hi:[1,0,1]
	v_pk_fma_f32 v[32:33], v[78:79], v[48:49], v[32:33] op_sel_hi:[1,0,1]
	v_pk_fma_f32 v[36:37], v[80:81], v[48:49], v[36:37] op_sel:[0,1,0]
	v_pk_fma_f32 v[38:39], v[82:83], v[48:49], v[38:39] op_sel:[0,1,0]
	v_pk_fma_f32 v[10:11], v[76:77], v[50:51], v[10:11] op_sel_hi:[1,0,1]
	v_pk_fma_f32 v[12:13], v[78:79], v[50:51], v[12:13] op_sel_hi:[1,0,1]
	v_pk_fma_f32 v[2:3], v[80:81], v[50:51], v[2:3] op_sel:[0,1,0]
	v_pk_fma_f32 v[4:5], v[82:83], v[50:51], v[4:5] op_sel:[0,1,0]
	ds_read_b128 v[44:47], v34 offset:17984
	ds_read_b128 v[48:51], v34 offset:18000
	s_waitcnt vmcnt(14) lgkmcnt(2)
	v_pk_fma_f32 v[18:19], v[88:89], v[14:15], v[18:19] op_sel_hi:[1,0,1]
	v_pk_fma_f32 v[20:21], v[90:91], v[14:15], v[20:21] op_sel_hi:[1,0,1]
	v_pk_fma_f32 v[22:23], v[92:93], v[14:15], v[22:23] op_sel:[0,1,0]
	v_pk_fma_f32 v[24:25], v[94:95], v[14:15], v[24:25] op_sel:[0,1,0]
	v_pk_fma_f32 v[26:27], v[88:89], v[16:17], v[26:27] op_sel_hi:[1,0,1]
	v_pk_fma_f32 v[28:29], v[90:91], v[16:17], v[28:29] op_sel_hi:[1,0,1]
	v_pk_fma_f32 v[6:7], v[92:93], v[16:17], v[6:7] op_sel:[0,1,0]
	v_pk_fma_f32 v[8:9], v[94:95], v[16:17], v[8:9] op_sel:[0,1,0]
	v_pk_fma_f32 v[30:31], v[88:89], v[40:41], v[30:31] op_sel_hi:[1,0,1]
	v_pk_fma_f32 v[32:33], v[90:91], v[40:41], v[32:33] op_sel_hi:[1,0,1]
	v_pk_fma_f32 v[36:37], v[92:93], v[40:41], v[36:37] op_sel:[0,1,0]
	v_pk_fma_f32 v[38:39], v[94:95], v[40:41], v[38:39] op_sel:[0,1,0]
	v_pk_fma_f32 v[10:11], v[88:89], v[42:43], v[10:11] op_sel_hi:[1,0,1]
	v_pk_fma_f32 v[12:13], v[90:91], v[42:43], v[12:13] op_sel_hi:[1,0,1]
	v_pk_fma_f32 v[2:3], v[92:93], v[42:43], v[2:3] op_sel:[0,1,0]
	v_pk_fma_f32 v[4:5], v[94:95], v[42:43], v[4:5] op_sel:[0,1,0]
	ds_read_b128 v[14:17], v34 offset:18048
	ds_read_b128 v[40:43], v34 offset:18064
	s_waitcnt vmcnt(12) lgkmcnt(2)
	v_pk_fma_f32 v[18:19], v[96:97], v[44:45], v[18:19] op_sel_hi:[1,0,1]
	v_pk_fma_f32 v[20:21], v[98:99], v[44:45], v[20:21] op_sel_hi:[1,0,1]
	v_pk_fma_f32 v[22:23], v[100:101], v[44:45], v[22:23] op_sel:[0,1,0]
	v_pk_fma_f32 v[24:25], v[102:103], v[44:45], v[24:25] op_sel:[0,1,0]
	v_pk_fma_f32 v[26:27], v[96:97], v[46:47], v[26:27] op_sel_hi:[1,0,1]
	v_pk_fma_f32 v[28:29], v[98:99], v[46:47], v[28:29] op_sel_hi:[1,0,1]
	v_pk_fma_f32 v[6:7], v[100:101], v[46:47], v[6:7] op_sel:[0,1,0]
	v_pk_fma_f32 v[8:9], v[102:103], v[46:47], v[8:9] op_sel:[0,1,0]
	v_pk_fma_f32 v[30:31], v[96:97], v[48:49], v[30:31] op_sel_hi:[1,0,1]
	v_pk_fma_f32 v[32:33], v[98:99], v[48:49], v[32:33] op_sel_hi:[1,0,1]
	v_pk_fma_f32 v[36:37], v[100:101], v[48:49], v[36:37] op_sel:[0,1,0]
	v_pk_fma_f32 v[38:39], v[102:103], v[48:49], v[38:39] op_sel:[0,1,0]
	v_pk_fma_f32 v[10:11], v[96:97], v[50:51], v[10:11] op_sel_hi:[1,0,1]
	v_pk_fma_f32 v[12:13], v[98:99], v[50:51], v[12:13] op_sel_hi:[1,0,1]
	v_pk_fma_f32 v[2:3], v[100:101], v[50:51], v[2:3] op_sel:[0,1,0]
	v_pk_fma_f32 v[4:5], v[102:103], v[50:51], v[4:5] op_sel:[0,1,0]
	ds_read_b128 v[44:47], v34 offset:18112
	ds_read_b128 v[48:51], v34 offset:18128
	s_waitcnt vmcnt(10) lgkmcnt(2)
	v_pk_fma_f32 v[18:19], v[104:105], v[14:15], v[18:19] op_sel_hi:[1,0,1]
	v_pk_fma_f32 v[20:21], v[106:107], v[14:15], v[20:21] op_sel_hi:[1,0,1]
	v_pk_fma_f32 v[22:23], v[108:109], v[14:15], v[22:23] op_sel:[0,1,0]
	v_pk_fma_f32 v[24:25], v[110:111], v[14:15], v[24:25] op_sel:[0,1,0]
	v_pk_fma_f32 v[26:27], v[104:105], v[16:17], v[26:27] op_sel_hi:[1,0,1]
	v_pk_fma_f32 v[28:29], v[106:107], v[16:17], v[28:29] op_sel_hi:[1,0,1]
	v_pk_fma_f32 v[6:7], v[108:109], v[16:17], v[6:7] op_sel:[0,1,0]
	v_pk_fma_f32 v[8:9], v[110:111], v[16:17], v[8:9] op_sel:[0,1,0]
	v_pk_fma_f32 v[30:31], v[104:105], v[40:41], v[30:31] op_sel_hi:[1,0,1]
	v_pk_fma_f32 v[32:33], v[106:107], v[40:41], v[32:33] op_sel_hi:[1,0,1]
	v_pk_fma_f32 v[36:37], v[108:109], v[40:41], v[36:37] op_sel:[0,1,0]
	v_pk_fma_f32 v[38:39], v[110:111], v[40:41], v[38:39] op_sel:[0,1,0]
	v_pk_fma_f32 v[10:11], v[104:105], v[42:43], v[10:11] op_sel_hi:[1,0,1]
	v_pk_fma_f32 v[12:13], v[106:107], v[42:43], v[12:13] op_sel_hi:[1,0,1]
	v_pk_fma_f32 v[2:3], v[108:109], v[42:43], v[2:3] op_sel:[0,1,0]
	v_pk_fma_f32 v[4:5], v[110:111], v[42:43], v[4:5] op_sel:[0,1,0]
	ds_read_b128 v[14:17], v34 offset:18176
	ds_read_b128 v[40:43], v34 offset:18192
	s_waitcnt vmcnt(8) lgkmcnt(2)
; #define DEC_LOADV(dst, i0) do { asm volatile("" ::: "memory"); _Pragma("unroll") for (int u = 0; u < 4; ++u) { const float* vr = cv + rbase + (size_t)((i0) + u) * 512; dst[u][0] = __builtin_nontemporal_load((const f32x4*)(vr + 4 * lane)); dst[u][1] = __builtin_nontemporal_load((const f32x4*)(vr + 256 + 4 * lane)); } } while (0)
; __device__ __forceinline__ void decode_item(Frame& F, const Args& a, int l, int item, unsigned char* ws) {
;     ...
;         DEC_LOADV(va, 0); DEC_LOADV(vb, 4); DEC_ACC(va, 0); DEC_LOADV(va, 8); DEC_ACC(vb, 4); DEC_LOADV(vb, 12); DEC_ACC(va, 8); DEC_LOADV(va, 16); DEC_ACC(vb, 12); DEC_LOADV(vb, 20); DEC_ACC(va, 16); DEC_LOADV(va, 24); DEC_ACC(vb, 20); DEC_LOADV(vb, 28); DEC_ACC(va, 24); DEC_ACC(vb, 28);
;     ...
;     }
;     __syncthreads();
	v_pk_fma_f32 v[18:19], v[184:185], v[44:45], v[18:19] op_sel_hi:[1,0,1]
	v_pk_fma_f32 v[20:21], v[186:187], v[44:45], v[20:21] op_sel_hi:[1,0,1]
	v_pk_fma_f32 v[22:23], v[188:189], v[44:45], v[22:23] op_sel:[0,1,0]
	v_pk_fma_f32 v[24:25], v[190:191], v[44:45], v[24:25] op_sel:[0,1,0]
	v_pk_fma_f32 v[26:27], v[184:185], v[46:47], v[26:27] op_sel_hi:[1,0,1]
	v_pk_fma_f32 v[28:29], v[186:187], v[46:47], v[28:29] op_sel_hi:[1,0,1]
	v_pk_fma_f32 v[6:7], v[188:189], v[46:47], v[6:7] op_sel:[0,1,0]
	v_pk_fma_f32 v[8:9], v[190:191], v[46:47], v[8:9] op_sel:[0,1,0]
	v_pk_fma_f32 v[30:31], v[184:185], v[48:49], v[30:31] op_sel_hi:[1,0,1]
	v_pk_fma_f32 v[32:33], v[186:187], v[48:49], v[32:33] op_sel_hi:[1,0,1]
	v_pk_fma_f32 v[36:37], v[188:189], v[48:49], v[36:37] op_sel:[0,1,0]
	v_pk_fma_f32 v[38:39], v[190:191], v[48:49], v[38:39] op_sel:[0,1,0]
	v_pk_fma_f32 v[10:11], v[184:185], v[50:51], v[10:11] op_sel_hi:[1,0,1]
	v_pk_fma_f32 v[12:13], v[186:187], v[50:51], v[12:13] op_sel_hi:[1,0,1]
	v_pk_fma_f32 v[2:3], v[188:189], v[50:51], v[2:3] op_sel:[0,1,0]
	v_pk_fma_f32 v[4:5], v[190:191], v[50:51], v[4:5] op_sel:[0,1,0]
	ds_read_b128 v[44:47], v34 offset:18240
	ds_read_b128 v[48:51], v34 offset:18256
	s_waitcnt vmcnt(6) lgkmcnt(2)
	v_pk_fma_f32 v[18:19], v[192:193], v[14:15], v[18:19] op_sel_hi:[1,0,1]
	v_pk_fma_f32 v[20:21], v[194:195], v[14:15], v[20:21] op_sel_hi:[1,0,1]
	v_pk_fma_f32 v[22:23], v[196:197], v[14:15], v[22:23] op_sel:[0,1,0]
	v_pk_fma_f32 v[24:25], v[198:199], v[14:15], v[24:25] op_sel:[0,1,0]
	v_pk_fma_f32 v[26:27], v[192:193], v[16:17], v[26:27] op_sel_hi:[1,0,1]
	v_pk_fma_f32 v[28:29], v[194:195], v[16:17], v[28:29] op_sel_hi:[1,0,1]
	v_pk_fma_f32 v[6:7], v[196:197], v[16:17], v[6:7] op_sel:[0,1,0]
	v_pk_fma_f32 v[8:9], v[198:199], v[16:17], v[8:9] op_sel:[0,1,0]
	v_pk_fma_f32 v[30:31], v[192:193], v[40:41], v[30:31] op_sel_hi:[1,0,1]
	v_pk_fma_f32 v[32:33], v[194:195], v[40:41], v[32:33] op_sel_hi:[1,0,1]
	v_pk_fma_f32 v[36:37], v[196:197], v[40:41], v[36:37] op_sel:[0,1,0]
	v_pk_fma_f32 v[38:39], v[198:199], v[40:41], v[38:39] op_sel:[0,1,0]
	v_pk_fma_f32 v[10:11], v[192:193], v[42:43], v[10:11] op_sel_hi:[1,0,1]
	v_pk_fma_f32 v[12:13], v[194:195], v[42:43], v[12:13] op_sel_hi:[1,0,1]
	v_pk_fma_f32 v[2:3], v[196:197], v[42:43], v[2:3] op_sel:[0,1,0]
	v_pk_fma_f32 v[4:5], v[198:199], v[42:43], v[4:5] op_sel:[0,1,0]
	ds_read_b128 v[14:17], v34 offset:18304
	ds_read_b128 v[40:43], v34 offset:18320
	s_waitcnt vmcnt(4) lgkmcnt(2)
	v_pk_fma_f32 v[18:19], v[200:201], v[44:45], v[18:19] op_sel_hi:[1,0,1]
	v_pk_fma_f32 v[20:21], v[202:203], v[44:45], v[20:21] op_sel_hi:[1,0,1]
	v_pk_fma_f32 v[22:23], v[204:205], v[44:45], v[22:23] op_sel:[0,1,0]
	v_pk_fma_f32 v[24:25], v[206:207], v[44:45], v[24:25] op_sel:[0,1,0]
	v_pk_fma_f32 v[26:27], v[200:201], v[46:47], v[26:27] op_sel_hi:[1,0,1]
	v_pk_fma_f32 v[28:29], v[202:203], v[46:47], v[28:29] op_sel_hi:[1,0,1]
	v_pk_fma_f32 v[6:7], v[204:205], v[46:47], v[6:7] op_sel:[0,1,0]
	v_pk_fma_f32 v[8:9], v[206:207], v[46:47], v[8:9] op_sel:[0,1,0]
	v_pk_fma_f32 v[30:31], v[200:201], v[48:49], v[30:31] op_sel_hi:[1,0,1]
	v_pk_fma_f32 v[32:33], v[202:203], v[48:49], v[32:33] op_sel_hi:[1,0,1]
	v_pk_fma_f32 v[36:37], v[204:205], v[48:49], v[36:37] op_sel:[0,1,0]
	v_pk_fma_f32 v[38:39], v[206:207], v[48:49], v[38:39] op_sel:[0,1,0]
	v_pk_fma_f32 v[10:11], v[200:201], v[50:51], v[10:11] op_sel_hi:[1,0,1]
	v_pk_fma_f32 v[12:13], v[202:203], v[50:51], v[12:13] op_sel_hi:[1,0,1]
	v_pk_fma_f32 v[2:3], v[204:205], v[50:51], v[2:3] op_sel:[0,1,0]
	v_pk_fma_f32 v[4:5], v[206:207], v[50:51], v[4:5] op_sel:[0,1,0]
	ds_read_b128 v[44:47], v34 offset:18368
	ds_read_b128 v[48:51], v34 offset:18384
	s_waitcnt vmcnt(2) lgkmcnt(2)
	v_pk_fma_f32 v[18:19], v[52:53], v[14:15], v[18:19] op_sel_hi:[1,0,1]
	v_pk_fma_f32 v[20:21], v[54:55], v[14:15], v[20:21] op_sel_hi:[1,0,1]
	v_pk_fma_f32 v[22:23], v[56:57], v[14:15], v[22:23] op_sel:[0,1,0]
	v_pk_fma_f32 v[24:25], v[58:59], v[14:15], v[24:25] op_sel:[0,1,0]
	v_pk_fma_f32 v[26:27], v[52:53], v[16:17], v[26:27] op_sel_hi:[1,0,1]
	v_pk_fma_f32 v[28:29], v[54:55], v[16:17], v[28:29] op_sel_hi:[1,0,1]
	v_pk_fma_f32 v[6:7], v[56:57], v[16:17], v[6:7] op_sel:[0,1,0]
	v_pk_fma_f32 v[8:9], v[58:59], v[16:17], v[8:9] op_sel:[0,1,0]
	v_pk_fma_f32 v[30:31], v[52:53], v[40:41], v[30:31] op_sel_hi:[1,0,1]
	v_pk_fma_f32 v[32:33], v[54:55], v[40:41], v[32:33] op_sel_hi:[1,0,1]
	v_pk_fma_f32 v[36:37], v[56:57], v[40:41], v[36:37] op_sel:[0,1,0]
	v_pk_fma_f32 v[38:39], v[58:59], v[40:41], v[38:39] op_sel:[0,1,0]
	v_pk_fma_f32 v[10:11], v[52:53], v[42:43], v[10:11] op_sel_hi:[1,0,1]
	v_pk_fma_f32 v[12:13], v[54:55], v[42:43], v[12:13] op_sel_hi:[1,0,1]
	v_pk_fma_f32 v[2:3], v[56:57], v[42:43], v[2:3] op_sel:[0,1,0]
	v_pk_fma_f32 v[4:5], v[58:59], v[42:43], v[4:5] op_sel:[0,1,0]
	s_waitcnt vmcnt(0) lgkmcnt(0)
	v_pk_fma_f32 v[18:19], v[60:61], v[44:45], v[18:19] op_sel_hi:[1,0,1]
	v_pk_fma_f32 v[20:21], v[62:63], v[44:45], v[20:21] op_sel_hi:[1,0,1]
	v_pk_fma_f32 v[22:23], v[64:65], v[44:45], v[22:23] op_sel:[0,1,0]
	v_pk_fma_f32 v[24:25], v[66:67], v[44:45], v[24:25] op_sel:[0,1,0]
	v_pk_fma_f32 v[26:27], v[60:61], v[46:47], v[26:27] op_sel_hi:[1,0,1]
	v_pk_fma_f32 v[28:29], v[62:63], v[46:47], v[28:29] op_sel_hi:[1,0,1]
	v_pk_fma_f32 v[6:7], v[64:65], v[46:47], v[6:7] op_sel:[0,1,0]
	v_pk_fma_f32 v[8:9], v[66:67], v[46:47], v[8:9] op_sel:[0,1,0]
	v_pk_fma_f32 v[30:31], v[60:61], v[48:49], v[30:31] op_sel_hi:[1,0,1]
	v_pk_fma_f32 v[32:33], v[62:63], v[48:49], v[32:33] op_sel_hi:[1,0,1]
	v_pk_fma_f32 v[36:37], v[64:65], v[48:49], v[36:37] op_sel:[0,1,0]
	v_pk_fma_f32 v[38:39], v[66:67], v[48:49], v[38:39] op_sel:[0,1,0]
	v_pk_fma_f32 v[10:11], v[60:61], v[50:51], v[10:11] op_sel_hi:[1,0,1]
	v_pk_fma_f32 v[12:13], v[62:63], v[50:51], v[12:13] op_sel_hi:[1,0,1]
	v_pk_fma_f32 v[2:3], v[64:65], v[50:51], v[2:3] op_sel:[0,1,0]
	v_pk_fma_f32 v[4:5], v[66:67], v[50:51], v[4:5] op_sel:[0,1,0]
	s_waitcnt lgkmcnt(0)
	s_barrier
; #define LAS __attribute__((address_space(3)))
; #define LDS_WAIT() asm volatile("s_waitcnt lgkmcnt(0)" ::: "memory")
; __device__ __forceinline__ void decode_item(Frame& F, const Args& a, int l, int item, unsigned char* ws) {
;     ...
;     __syncthreads();
;     LAS float* RED = (LAS float*)F.lds;
; #pragma unroll
;     for (int qi = 0; qi < 4; ++qi)
; #pragma unroll
;         for (int g = 0; g < 2; ++g) { LAS float* d = RED + ((w * 16 + qi * 4 + g * 2 + hh) * 128 + 4 * (lane & 31)); d[0] = O[qi][g][0]; d[1] = O[qi][g][1]; d[2] = O[qi][g][2]; d[3] = O[qi][g][3]; }
;     LDS_WAIT(); __syncthreads();
;     { f32x4 s = (f32x4){0.f, 0.f, 0.f, 0.f};
; #pragma unroll
;       for (int j = 0; j < 8; ++j) { const LAS float* p = RED + j * 2048 + tid * 4; s += (f32x4){p[0], p[1], p[2], p[3]}; }
;       *(f32x4*)((float*)(ws + WS_OSEG) + (size_t)(sb * 64 + seg) * 2048 + tid * 4) = s; }
	v_and_b32_e32 v14, 0x7c, v116
	v_lshl_add_u32 v14, v14, 2, 0
	v_lshlrev_b32_e64 v15, 13, s18
	v_lshlrev_b32_e32 v16, 9, v124
	v_add3_u32 v14, v14, v15, v16
	ds_write_b128 v14, v[18:21]
	ds_write_b128 v14, v[22:25] offset:1024
	ds_write_b128 v14, v[26:29] offset:2048
	ds_write_b128 v14, v[6:9] offset:3072
	ds_write_b128 v14, v[30:33] offset:4096
	ds_write_b128 v14, v[36:39] offset:5120
	ds_write_b128 v14, v[10:13] offset:6144
	ds_write_b128 v14, v[2:5] offset:7168
	v_lshl_add_u32 v10, v1, 4, 0
	s_waitcnt lgkmcnt(0)
	s_waitcnt lgkmcnt(0)
	s_barrier
	ds_read_b128 v[2:5], v10
	s_waitcnt lgkmcnt(0)
	v_pk_add_f32 v[6:7], v[4:5], 0 op_sel_hi:[1,0]
	v_pk_add_f32 v[8:9], v[2:3], 0 op_sel_hi:[1,0]
	ds_read_b128 v[2:5], v10 offset:8192
	s_waitcnt lgkmcnt(0)
	v_pk_add_f32 v[6:7], v[6:7], v[4:5]
	v_pk_add_f32 v[8:9], v[8:9], v[2:3]
	ds_read_b128 v[2:5], v10 offset:16384
	s_waitcnt lgkmcnt(0)
	v_pk_add_f32 v[6:7], v[6:7], v[4:5]
	v_pk_add_f32 v[8:9], v[8:9], v[2:3]
	ds_read_b128 v[2:5], v10 offset:24576
	s_waitcnt lgkmcnt(0)
	v_pk_add_f32 v[6:7], v[6:7], v[4:5]
	v_pk_add_f32 v[8:9], v[8:9], v[2:3]
	ds_read_b128 v[2:5], v10 offset:32768
	s_waitcnt lgkmcnt(0)
	v_pk_add_f32 v[6:7], v[6:7], v[4:5]
	v_pk_add_f32 v[8:9], v[8:9], v[2:3]
	ds_read_b128 v[2:5], v10 offset:40960
	s_waitcnt lgkmcnt(0)
	v_pk_add_f32 v[6:7], v[6:7], v[4:5]
	v_pk_add_f32 v[8:9], v[8:9], v[2:3]
	ds_read_b128 v[2:5], v10 offset:49152
	s_waitcnt lgkmcnt(0)
	v_pk_add_f32 v[6:7], v[6:7], v[4:5]
	v_pk_add_f32 v[8:9], v[8:9], v[2:3]
	ds_read_b128 v[2:5], v10 offset:57344
	s_waitcnt lgkmcnt(0)
	v_pk_add_f32 v[4:5], v[6:7], v[4:5]
	v_pk_add_f32 v[2:3], v[8:9], v[2:3]
	v_lshlrev_b64 v[6:7], 13, v[84:85]
	v_lshlrev_b32_e32 v8, 2, v1
	v_lshl_add_u64 v[6:7], s[10:11], 0, v[6:7]
	v_ashrrev_i32_e32 v9, 31, v8
	v_lshl_add_u64 v[6:7], v[8:9], 2, v[6:7]
	v_add_co_u32_e32 v6, vcc, 0x34700000, v6
	s_nop 1
	v_addc_co_u32_e32 v7, vcc, 0, v7, vcc
	global_store_dwordx4 v[6:7], v[2:5], off
	s_barrier
	s_cbranch_execnz .LBB0_1031
	s_branch .LBB0_1048
